# f2 + attention stagger: waves 4-7 run exp/PV of tile j after the barrier (beside partner QK) with static priority raise
# speedup vs baseline: 1.0056x; 1.0056x over previous
; __device__ __forceinline__ void attn_item(LAS unsigned char* lds, int b, int h, int qb, const bf16_t* Q, const bf16_t* KN, const bf16_t* KR, const bf16_t* VT, bf16_t* MIXIN, float* STAT2) {
;     const int tid = threadIdx.x, lane = tid & 63, w = __builtin_amdgcn_readfirstlane(tid >> 6), c = lane & 31, hi = lane >> 5;
;     const int bh = b * 8 + h;
;     constexpr int KP = 400, KB = 64 * KP, VP = 144, VB = 128 * VP, VOFF = 2 * KB;
;     bf16x8 qf[12];
;     { const bf16_t* qp = Q + ((size_t)bh * 4096 + qb * 256 + w * 32 + c) * 192 + 8 * hi;
; #pragma unroll
;         for (int ks = 0; ks < 12; ++ks) qf[ks] = *(const bf16x8*)(qp + 16 * ks);
;  }
;     const bf16_t* knb = KN + (size_t)bh * 4096 * 128; const bf16_t* krb = KR + (size_t)b * 4096 * 64; const bf16_t* vtb = VT + (size_t)bh * 128 * 4096;
;     u32x4 rk0, rk1, rr, rv0, rv1;
;     const int n_row0 = tid >> 4, n_ch = tid & 15, r_row = tid >> 3, r_ch = tid & 7, v_d0 = tid >> 3, v_ch = tid & 7;
;     ...
;     float mrow = -1e30f, lrow = 0.f;
;     f32x16 oT[4];
; #pragma unroll
;     for (int d = 0; d < 4; ++d)
; #pragma unroll
;         for (int r = 0; r < 16; ++r) oT[d][r] = 0.f;
;     const int NT = 4 * (qb + 1);
;     AT_LOAD(0);
; #pragma unroll
;     for (int ks = 0; ks < 12; ++ks) asm volatile("" : "+v"(qf[ks]));
;     AT_STORE(0, 0);
;     __syncthreads();
;     int vprev = 0, vcur = 0;
.LBB0_958:
	s_mov_b32 s90, 0
	s_add_i32 s8, s66, 0xffffff80
	s_ashr_i32 s33, s8, 6
	v_readfirstlane_b32 s12, v183
	s_sub_i32 s34, 15, s33
	s_lshr_b32 s35, s12, 1
	s_lshl_b32 s13, s34, 8
	s_and_b32 s44, s35, 0x7fffffe0
	s_and_b32 s14, s66, 63
	s_add_i32 s12, s44, s13
	s_lshl_b32 s8, s14, 12
	v_or_b32_e32 v202, s12, v182
	v_mov_b32_e32 v203, v1
	v_lshl_add_u64 v[4:5], v[202:203], 0, s[8:9]
	v_mad_u64_u32 v[6:7], s[12:13], v4, s24, v[184:185]
	s_lshl_b32 s12, s66, 9
	s_and_b32 s12, s12, 0x7000
	s_lshl_b32 s8, s14, 20
	s_lshl_b32 s13, s12, 7
	s_add_u32 s14, s20, s13
	s_addc_u32 s15, s21, 0
	s_add_u32 s16, s18, s8
	s_addc_u32 s17, s19, 0
	s_add_u32 s30, s22, s8
	v_lshl_add_u64 v[8:9], s[16:17], 0, v[196:197]
	v_mad_u32_u24 v7, v5, s24, v7
	s_addc_u32 s31, s23, 0
	v_lshl_add_u64 v[4:5], s[16:17], 0, v[192:193]
	v_lshl_add_u64 v[8:9], v[8:9], 0, v[194:195]
	v_lshl_add_u64 v[10:11], s[14:15], 0, v[186:187]
	v_lshl_add_u64 v[4:5], v[4:5], 0, v[194:195]
	v_lshl_add_u64 v[10:11], v[10:11], 0, v[198:199]
	global_load_dwordx4 v[122:125], v[8:9], off
	global_load_dwordx4 v[170:173], v[10:11], off
	v_lshl_add_u64 v[8:9], s[30:31], 0, v[188:189]
	v_lshl_add_u64 v[204:205], v[8:9], 0, v[198:199]
	global_load_dwordx4 v[138:141], v[4:5], off
	global_load_dwordx4 v[174:177], v[204:205], off
	v_lshl_add_u64 v[4:5], s[30:31], 0, v[200:201]
	v_lshl_add_u64 v[10:11], v[4:5], 0, v[198:199]
	v_add_co_u32_e32 v4, vcc, s25, v10
	global_load_dwordx4 v[114:117], v[6:7], off
	global_load_dwordx4 v[118:121], v[6:7], off offset:32
	global_load_dwordx4 v[126:129], v[6:7], off offset:64
	global_load_dwordx4 v[130:133], v[6:7], off offset:96
	global_load_dwordx4 v[134:137], v[6:7], off offset:128
	global_load_dwordx4 v[142:145], v[6:7], off offset:160
	global_load_dwordx4 v[146:149], v[6:7], off offset:192
	global_load_dwordx4 v[150:153], v[6:7], off offset:224
	global_load_dwordx4 v[154:157], v[6:7], off offset:256
	global_load_dwordx4 v[158:161], v[6:7], off offset:288
	global_load_dwordx4 v[162:165], v[6:7], off offset:320
	global_load_dwordx4 v[166:169], v[6:7], off offset:352
	v_addc_co_u32_e32 v5, vcc, 0, v11, vcc
	global_load_dwordx4 v[178:181], v[4:5], off
	v_mov_b32_e32 v16, v3
	v_mov_b32_e32 v17, v3
	v_mov_b32_e32 v2, v3
	v_mov_b32_e32 v4, v3
	v_mov_b32_e32 v5, v3
	v_mov_b32_e32 v6, v3
	v_mov_b32_e32 v7, v3
	v_mov_b32_e32 v8, v3
	v_mov_b32_e32 v9, v3
	s_lshl_b32 s34, s34, 2
	s_lshl_b32 s31, s33, 8
	v_lshl_add_u64 v[210:211], v[10:11], 0, s[10:11]
	v_mov_b32_e32 v10, v3
	v_mov_b32_e32 v11, v3
	v_mov_b32_e32 v12, v3
	v_mov_b32_e32 v13, v3
	v_mov_b32_e32 v14, v3
	v_mov_b32_e32 v15, v3
	v_mov_b64_e32 v[32:33], v[16:17]
	v_mov_b64_e32 v[48:49], v[16:17]
	v_mov_b64_e32 v[64:65], v[16:17]
	v_mov_b64_e32 v[80:81], v[16:17]
	s_mov_b32 s13, s9
	v_or_b32_e32 v227, s44, v182
	v_lshl_add_u64 v[206:207], s[14:15], 0, v[198:199]
	v_lshl_add_u64 v[208:209], s[16:17], 0, v[194:195]
	s_or_b32 s30, s35, 31
	s_cmp_lt_i32 s30, 0x9f
	s_cbranch_scc1 .Latt_noprio
	s_setprio 1
.Latt_noprio:
	s_lshl_b32 s33, s33, 2
	s_add_i32 s34, s34, 4
	v_or_b32_e32 v228, s31, v190
	s_mov_b32 s35, s9
	s_mov_b32 s44, 1
	v_mov_b64_e32 v[30:31], v[14:15]
	v_mov_b64_e32 v[28:29], v[12:13]
	v_mov_b64_e32 v[26:27], v[10:11]
	v_mov_b64_e32 v[24:25], v[8:9]
	v_mov_b64_e32 v[22:23], v[6:7]
	v_mov_b64_e32 v[20:21], v[4:5]
	v_mov_b64_e32 v[18:19], v[2:3]
	v_mov_b64_e32 v[46:47], v[14:15]
	v_mov_b64_e32 v[44:45], v[12:13]
	v_mov_b64_e32 v[42:43], v[10:11]
	v_mov_b64_e32 v[40:41], v[8:9]
	v_mov_b64_e32 v[38:39], v[6:7]
	v_mov_b64_e32 v[36:37], v[4:5]
	v_mov_b64_e32 v[34:35], v[2:3]
	v_mov_b64_e32 v[62:63], v[14:15]
	v_mov_b64_e32 v[60:61], v[12:13]
	v_mov_b64_e32 v[58:59], v[10:11]
	v_mov_b64_e32 v[56:57], v[8:9]
	v_mov_b64_e32 v[54:55], v[6:7]
	v_mov_b64_e32 v[52:53], v[4:5]
	v_mov_b64_e32 v[50:51], v[2:3]
	v_mov_b64_e32 v[78:79], v[14:15]
	v_mov_b64_e32 v[76:77], v[12:13]
	v_mov_b64_e32 v[74:75], v[10:11]
	v_mov_b64_e32 v[72:73], v[8:9]
	v_mov_b64_e32 v[70:71], v[6:7]
	v_mov_b64_e32 v[68:69], v[4:5]
	v_mov_b64_e32 v[66:67], v[2:3]
	v_mov_b32_e32 v4, 0xf149f2ca
	s_mov_b32 s45, s9
	s_waitcnt vmcnt(12)
	s_waitcnt vmcnt(11)
	s_waitcnt vmcnt(10)
	s_waitcnt vmcnt(9)
	s_waitcnt vmcnt(8)
	s_waitcnt vmcnt(7)
	s_waitcnt vmcnt(6)
	s_waitcnt vmcnt(5)
	s_waitcnt vmcnt(4)
	s_waitcnt vmcnt(3)
	s_waitcnt vmcnt(2)
	s_waitcnt vmcnt(1)
	ds_write_b128 v222, v[138:141]
	ds_write_b128 v222, v[122:125] offset:12800
	ds_write_b128 v223, v[170:173] offset:256
	ds_write2_b64 v224, v[174:175], v[176:177] offset1:2
	s_waitcnt vmcnt(0)
	ds_write2_b64 v225, v[178:179], v[180:181] offset0:128 offset1:130
	s_waitcnt lgkmcnt(0)
	s_barrier
	s_branch .LBB0_960

; #define LAS __attribute__((address_space(3)))
; #define MFMA32(a, b, c) __builtin_amdgcn_mfma_f32_32x32x16_bf16((a), (b), (c), 0, 0, 0)
; #define AT_EXP2(P, r) do { f32x2 dd = (f32x2){P[r], P[(r) + 1]} - mm; dd.x = __builtin_amdgcn_exp2f(dd.x); dd.y = __builtin_amdgcn_exp2f(dd.y); ssum += dd; P[r] = dd.x; P[(r) + 1] = dd.y; } while (0)
; #define AT_PACK(P, b8) ((u32x4){cvt_pk_bf16(P[(b8)], P[(b8) + 1]), cvt_pk_bf16(P[(b8) + 2], P[(b8) + 3]), cvt_pk_bf16(P[(b8) + 4], P[(b8) + 5]), cvt_pk_bf16(P[(b8) + 6], P[(b8) + 7])})
; __device__ __forceinline__ void attn_item(LAS unsigned char* lds, int b, int h, int qb, const bf16_t* Q, const bf16_t* KN, const bf16_t* KR, const bf16_t* VT, bf16_t* MIXIN, float* STAT2) {
;     ...
;             {
;                 const f32x2 mm = (f32x2){mrow, mrow}; f32x2 ssum = (f32x2){0.f, 0.f};
;                 const LAS unsigned char* vbase = lds + VOFF + vcur * VB + c * VP + hi * 16;
;     ...
; #pragma unroll
;                 for (int kk = 0; kk < 4; ++kk) {
;                     const bf16x8 vf0 = *(const LAS bf16x8*)(vbase + kk * 32), vf1 = *(const LAS bf16x8*)(vbase + 32 * VP + kk * 32);
;                     __builtin_amdgcn_sched_barrier(0);
;                     bf16x8 pfk;
;                     if (kk < 2) { AT_EXP2(p0, 8 * kk); AT_EXP2(p0, 8 * kk + 2); AT_EXP2(p0, 8 * kk + 4); AT_EXP2(p0, 8 * kk + 6); pfk = __builtin_bit_cast(bf16x8, AT_PACK(p0, 8 * kk)); }
;                     else { const int k2 = kk - 2; AT_EXP2(p1, 8 * k2); AT_EXP2(p1, 8 * k2 + 2); AT_EXP2(p1, 8 * k2 + 4); AT_EXP2(p1, 8 * k2 + 6); pfk = __builtin_bit_cast(bf16x8, AT_PACK(p1, 8 * k2)); }
;                     { const bf16x8 vf2 = *(const LAS bf16x8*)(vbase + 64 * VP + kk * 32), vf3 = *(const LAS bf16x8*)(vbase + 96 * VP + kk * 32);
;                       oT[0] = MFMA32(vf0, pfk, oT[0]); oT[1] = MFMA32(vf1, pfk, oT[1]); oT[2] = MFMA32(vf2, pfk, oT[2]); oT[3] = MFMA32(vf3, pfk, oT[3]); }
;                     __builtin_amdgcn_sched_barrier(0);
;                 }
;     ...
;                 lrow += ssum.x + ssum.y; }
.LBB0_962:
	s_cmp_eq_u32 s90, 0
	s_cbranch_scc1 .Latt_nopend
	s_mul_i32 s8, s91, 0x4800
	v_add_u32_e32 v2, s8, v220
	ds_read_b128 v[6:9], v2 offset:51200
	ds_read_b128 v[10:13], v2 offset:55808
	v_sub_f32_e32 v14, v98, v4
	v_sub_f32_e32 v15, v99, v4
	v_exp_f32_e32 v98, v14
	v_exp_f32_e32 v99, v15
	v_sub_f32_e32 v14, v100, v4
	v_sub_f32_e32 v15, v101, v4
	v_exp_f32_e32 v100, v14
	v_exp_f32_e32 v101, v15
	v_sub_f32_e32 v14, v102, v4
	v_sub_f32_e32 v15, v103, v4
	v_exp_f32_e32 v102, v14
	v_exp_f32_e32 v103, v15
	v_sub_f32_e32 v14, v104, v4
	v_sub_f32_e32 v15, v105, v4
	v_cvt_pk_bf16_f32 v16, v102, v103
	v_exp_f32_e32 v104, v14
	v_exp_f32_e32 v105, v15
	v_cvt_pk_bf16_f32 v14, v98, v99
	v_cvt_pk_bf16_f32 v15, v100, v101
	v_cvt_pk_bf16_f32 v17, v104, v105
	s_waitcnt lgkmcnt(1)
	s_nop 0
	v_mfma_f32_32x32x16_bf16 v[66:81], v[6:9], v[14:17], v[66:81]
	s_waitcnt lgkmcnt(0)
	v_mfma_f32_32x32x16_bf16 v[50:65], v[10:13], v[14:17], v[50:65]
	ds_read_b128 v[6:9], v2 offset:60416
	ds_read_b128 v[10:13], v2 offset:65024
	s_waitcnt lgkmcnt(1)
	v_mfma_f32_32x32x16_bf16 v[34:49], v[6:9], v[14:17], v[34:49]
	s_waitcnt lgkmcnt(0)
	v_mfma_f32_32x32x16_bf16 v[18:33], v[10:13], v[14:17], v[18:33]
	ds_read_b128 v[6:9], v2 offset:51232
	ds_read_b128 v[10:13], v2 offset:55840
	v_add_f32_e64 v14, v106, -v4
	v_add_f32_e64 v15, v107, -v4
	v_exp_f32_e32 v106, v14
	v_exp_f32_e32 v107, v15
	v_sub_f32_e32 v14, v108, v4
	v_sub_f32_e32 v15, v109, v4
	v_exp_f32_e32 v108, v14
	v_exp_f32_e32 v109, v15
	v_sub_f32_e32 v14, v110, v4
	v_sub_f32_e32 v15, v111, v4
	v_exp_f32_e32 v110, v14
	v_exp_f32_e32 v111, v15
	v_sub_f32_e32 v14, v112, v4
	v_sub_f32_e32 v15, v113, v4
	v_cvt_pk_bf16_f32 v16, v110, v111
	v_exp_f32_e32 v112, v14
	v_exp_f32_e32 v113, v15
	v_cvt_pk_bf16_f32 v14, v106, v107
	v_cvt_pk_bf16_f32 v15, v108, v109
	v_cvt_pk_bf16_f32 v17, v112, v113
	s_waitcnt lgkmcnt(1)
	s_nop 0
	v_mfma_f32_32x32x16_bf16 v[66:81], v[6:9], v[14:17], v[66:81]
	s_waitcnt lgkmcnt(0)
	v_mfma_f32_32x32x16_bf16 v[50:65], v[10:13], v[14:17], v[50:65]
	ds_read_b128 v[6:9], v2 offset:60448
	ds_read_b128 v[10:13], v2 offset:65056
	s_waitcnt lgkmcnt(1)
	v_mfma_f32_32x32x16_bf16 v[34:49], v[6:9], v[14:17], v[34:49]
	s_waitcnt lgkmcnt(0)
	v_mfma_f32_32x32x16_bf16 v[18:33], v[10:13], v[14:17], v[18:33]
	ds_read_b128 v[6:9], v2 offset:51264
	ds_read_b128 v[10:13], v2 offset:55872
	v_add_f32_e64 v14, v82, -v4
	v_add_f32_e64 v15, v83, -v4
	v_exp_f32_e32 v82, v14
	v_exp_f32_e32 v83, v15
	v_sub_f32_e32 v14, v84, v4
	v_sub_f32_e32 v15, v85, v4
	v_exp_f32_e32 v84, v14
	v_exp_f32_e32 v85, v15
	v_sub_f32_e32 v14, v86, v4
	v_sub_f32_e32 v15, v87, v4
	v_exp_f32_e32 v86, v14
	v_exp_f32_e32 v87, v15
	v_sub_f32_e32 v14, v88, v4
	v_sub_f32_e32 v15, v89, v4
	v_cvt_pk_bf16_f32 v16, v86, v87
	v_exp_f32_e32 v88, v14
	v_exp_f32_e32 v89, v15
	v_cvt_pk_bf16_f32 v14, v82, v83
	v_cvt_pk_bf16_f32 v15, v84, v85
	v_cvt_pk_bf16_f32 v17, v88, v89
	s_waitcnt lgkmcnt(1)
	s_nop 0
	v_mfma_f32_32x32x16_bf16 v[66:81], v[6:9], v[14:17], v[66:81]
	s_waitcnt lgkmcnt(0)
	v_mfma_f32_32x32x16_bf16 v[50:65], v[10:13], v[14:17], v[50:65]
	ds_read_b128 v[6:9], v2 offset:60480
	ds_read_b128 v[10:13], v2 offset:65088
	s_waitcnt lgkmcnt(1)
	v_mfma_f32_32x32x16_bf16 v[34:49], v[6:9], v[14:17], v[34:49]
	s_waitcnt lgkmcnt(0)
	v_mfma_f32_32x32x16_bf16 v[18:33], v[10:13], v[14:17], v[18:33]
	ds_read_b128 v[6:9], v2 offset:51296
	ds_read_b128 v[10:13], v2 offset:55904
	v_add_f32_e64 v14, v90, -v4
	v_add_f32_e64 v15, v91, -v4
	v_exp_f32_e32 v90, v14
	v_exp_f32_e32 v91, v15
	v_sub_f32_e32 v14, v92, v4
	v_sub_f32_e32 v15, v93, v4
	v_exp_f32_e32 v92, v14
	v_exp_f32_e32 v93, v15
	v_sub_f32_e32 v14, v94, v4
	v_sub_f32_e32 v15, v95, v4
	v_exp_f32_e32 v94, v14
	v_exp_f32_e32 v95, v15
	v_sub_f32_e32 v14, v96, v4
	v_sub_f32_e32 v15, v97, v4
	v_cvt_pk_bf16_f32 v16, v94, v95
	v_exp_f32_e32 v96, v14
	v_exp_f32_e32 v97, v15
	v_cvt_pk_bf16_f32 v14, v90, v91
	v_cvt_pk_bf16_f32 v15, v92, v93
	v_cvt_pk_bf16_f32 v17, v96, v97
	s_waitcnt lgkmcnt(1)
	s_nop 0
	v_mfma_f32_32x32x16_bf16 v[66:81], v[6:9], v[14:17], v[66:81]
	v_add_f32_e64 v6, v98, 0
	v_add_f32_e64 v7, v99, 0
	v_add_f32_e32 v6, v100, v6
	v_add_f32_e32 v7, v101, v7
	v_add_f32_e32 v98, v102, v6
	v_add_f32_e32 v99, v103, v7
	ds_read_b128 v[6:9], v2 offset:60512
	s_waitcnt lgkmcnt(1)
	v_mfma_f32_32x32x16_bf16 v[50:65], v[10:13], v[14:17], v[50:65]
	v_add_f32_e32 v10, v104, v98
	v_add_f32_e32 v11, v105, v99
	v_add_f32_e32 v10, v106, v10
	v_add_f32_e32 v11, v107, v11
	v_add_f32_e32 v10, v108, v10
	v_add_f32_e32 v11, v109, v11
	v_add_f32_e32 v10, v110, v10
	v_add_f32_e32 v11, v111, v11
	v_add_f32_e32 v10, v112, v10
	v_add_f32_e32 v11, v113, v11
	v_add_f32_e32 v82, v82, v10
	v_add_f32_e32 v83, v83, v11
	ds_read_b128 v[10:13], v2 offset:65120
	s_waitcnt lgkmcnt(1)
	v_mfma_f32_32x32x16_bf16 v[34:49], v[6:9], v[14:17], v[34:49]
	v_add_f32_e32 v6, v84, v82
	v_add_f32_e32 v7, v85, v83
	v_add_f32_e32 v6, v86, v6
	v_add_f32_e32 v7, v87, v7
	v_add_f32_e32 v6, v88, v6
	v_add_f32_e32 v7, v89, v7
	v_add_f32_e32 v6, v90, v6
	v_add_f32_e32 v7, v91, v7
	s_waitcnt lgkmcnt(0)
	v_mfma_f32_32x32x16_bf16 v[18:33], v[10:13], v[14:17], v[18:33]
	v_add_f32_e32 v6, v92, v6
	v_add_f32_e32 v7, v93, v7
	v_add_f32_e32 v6, v94, v6
	v_add_f32_e32 v7, v95, v7
	v_add_f32_e32 v6, v96, v6
	v_add_f32_e32 v7, v97, v7
	v_add_f32_e32 v2, v6, v7
	v_add_f32_e32 v5, v5, v2
	s_mov_b32 s90, 0

; #define LAS __attribute__((address_space(3)))
; __device__ __forceinline__ void attn_item(LAS unsigned char* lds, int b, int h, int qb, const bf16_t* Q, const bf16_t* KN, const bf16_t* KR, const bf16_t* VT, bf16_t* MIXIN, float* STAT2) {
;     ...
;         const int vnext = (vcur == 2) ? 0 : vcur + 1;
;         if (j + 1 < NT) AT_LOAD(j + 1);
;         const int jb = j - (NT - 4);
;         if (!(jb >= 0 && 64 * jb > 32 * w + 31)) {
;     ...
;             {
;                 const f32x2 mm = (f32x2){mrow, mrow}; f32x2 ssum = (f32x2){0.f, 0.f};
;                 const LAS unsigned char* vbase = lds + VOFF + vcur * VB + c * VP + hi * 16;
.LBB0_967:
	s_cmp_lt_i32 s30, 0x9f
	s_cbranch_scc1 .Latt_doB
	s_mov_b32 s90, 1
	s_mov_b32 s91, s45
	s_branch .LBB0_968

; #define LAS __attribute__((address_space(3)))
; #define MFMA32(a, b, c) __builtin_amdgcn_mfma_f32_32x32x16_bf16((a), (b), (c), 0, 0, 0)
; #define AT_EXP2(P, r) do { f32x2 dd = (f32x2){P[r], P[(r) + 1]} - mm; dd.x = __builtin_amdgcn_exp2f(dd.x); dd.y = __builtin_amdgcn_exp2f(dd.y); ssum += dd; P[r] = dd.x; P[(r) + 1] = dd.y; } while (0)
; #define AT_PACK(P, b8) ((u32x4){cvt_pk_bf16(P[(b8)], P[(b8) + 1]), cvt_pk_bf16(P[(b8) + 2], P[(b8) + 3]), cvt_pk_bf16(P[(b8) + 4], P[(b8) + 5]), cvt_pk_bf16(P[(b8) + 6], P[(b8) + 7])})
; __device__ __forceinline__ void attn_item(LAS unsigned char* lds, int b, int h, int qb, const bf16_t* Q, const bf16_t* KN, const bf16_t* KR, const bf16_t* VT, bf16_t* MIXIN, float* STAT2) {
;     ...
;             {
;                 const f32x2 mm = (f32x2){mrow, mrow}; f32x2 ssum = (f32x2){0.f, 0.f};
;                 const LAS unsigned char* vbase = lds + VOFF + vcur * VB + c * VP + hi * 16;
;     ...
; #pragma unroll
;                 for (int kk = 0; kk < 4; ++kk) {
;                     const bf16x8 vf0 = *(const LAS bf16x8*)(vbase + kk * 32), vf1 = *(const LAS bf16x8*)(vbase + 32 * VP + kk * 32);
;                     __builtin_amdgcn_sched_barrier(0);
;                     bf16x8 pfk;
;                     if (kk < 2) { AT_EXP2(p0, 8 * kk); AT_EXP2(p0, 8 * kk + 2); AT_EXP2(p0, 8 * kk + 4); AT_EXP2(p0, 8 * kk + 6); pfk = __builtin_bit_cast(bf16x8, AT_PACK(p0, 8 * kk)); }
;                     else { const int k2 = kk - 2; AT_EXP2(p1, 8 * k2); AT_EXP2(p1, 8 * k2 + 2); AT_EXP2(p1, 8 * k2 + 4); AT_EXP2(p1, 8 * k2 + 6); pfk = __builtin_bit_cast(bf16x8, AT_PACK(p1, 8 * k2)); }
;                     { const bf16x8 vf2 = *(const LAS bf16x8*)(vbase + 64 * VP + kk * 32), vf3 = *(const LAS bf16x8*)(vbase + 96 * VP + kk * 32);
;                       oT[0] = MFMA32(vf0, pfk, oT[0]); oT[1] = MFMA32(vf1, pfk, oT[1]); oT[2] = MFMA32(vf2, pfk, oT[2]); oT[3] = MFMA32(vf3, pfk, oT[3]); }
;                     __builtin_amdgcn_sched_barrier(0);
;                 }
;     ...
;                 lrow += ssum.x + ssum.y; }
;     ...
;     { const float lt = lrow + __shfl_xor(lrow, 32), inv = 1.0f / lt;
;         bf16_t* op = MIXIN + ((size_t)b * 4096 + qb * 256 + w * 32 + c) * DM + h * 128 + 4 * hi;
.LBB0_970:
	s_setprio 0
	s_cmp_eq_u32 s90, 0
	s_cbranch_scc1 .Latt_nodrain
	s_mul_i32 s8, s91, 0x4800
	v_add_u32_e32 v2, s8, v220
	ds_read_b128 v[6:9], v2 offset:51200
	ds_read_b128 v[10:13], v2 offset:55808
	v_sub_f32_e32 v14, v98, v4
	v_sub_f32_e32 v15, v99, v4
	v_exp_f32_e32 v98, v14
	v_exp_f32_e32 v99, v15
	v_sub_f32_e32 v14, v100, v4
	v_sub_f32_e32 v15, v101, v4
	v_exp_f32_e32 v100, v14
	v_exp_f32_e32 v101, v15
	v_sub_f32_e32 v14, v102, v4
	v_sub_f32_e32 v15, v103, v4
	v_exp_f32_e32 v102, v14
	v_exp_f32_e32 v103, v15
	v_sub_f32_e32 v14, v104, v4
	v_sub_f32_e32 v15, v105, v4
	v_cvt_pk_bf16_f32 v16, v102, v103
	v_exp_f32_e32 v104, v14
	v_exp_f32_e32 v105, v15
	v_cvt_pk_bf16_f32 v14, v98, v99
	v_cvt_pk_bf16_f32 v15, v100, v101
	v_cvt_pk_bf16_f32 v17, v104, v105
	s_waitcnt lgkmcnt(1)
	s_nop 0
	v_mfma_f32_32x32x16_bf16 v[66:81], v[6:9], v[14:17], v[66:81]
	s_waitcnt lgkmcnt(0)
	v_mfma_f32_32x32x16_bf16 v[50:65], v[10:13], v[14:17], v[50:65]
	ds_read_b128 v[6:9], v2 offset:60416
	ds_read_b128 v[10:13], v2 offset:65024
	s_waitcnt lgkmcnt(1)
	v_mfma_f32_32x32x16_bf16 v[34:49], v[6:9], v[14:17], v[34:49]
	s_waitcnt lgkmcnt(0)
	v_mfma_f32_32x32x16_bf16 v[18:33], v[10:13], v[14:17], v[18:33]
	ds_read_b128 v[6:9], v2 offset:51232
	ds_read_b128 v[10:13], v2 offset:55840
	v_add_f32_e64 v14, v106, -v4
	v_add_f32_e64 v15, v107, -v4
	v_exp_f32_e32 v106, v14
	v_exp_f32_e32 v107, v15
	v_sub_f32_e32 v14, v108, v4
	v_sub_f32_e32 v15, v109, v4
	v_exp_f32_e32 v108, v14
	v_exp_f32_e32 v109, v15
	v_sub_f32_e32 v14, v110, v4
	v_sub_f32_e32 v15, v111, v4
	v_exp_f32_e32 v110, v14
	v_exp_f32_e32 v111, v15
	v_sub_f32_e32 v14, v112, v4
	v_sub_f32_e32 v15, v113, v4
	v_cvt_pk_bf16_f32 v16, v110, v111
	v_exp_f32_e32 v112, v14
	v_exp_f32_e32 v113, v15
	v_cvt_pk_bf16_f32 v14, v106, v107
	v_cvt_pk_bf16_f32 v15, v108, v109
	v_cvt_pk_bf16_f32 v17, v112, v113
	s_waitcnt lgkmcnt(1)
	s_nop 0
	v_mfma_f32_32x32x16_bf16 v[66:81], v[6:9], v[14:17], v[66:81]
	s_waitcnt lgkmcnt(0)
	v_mfma_f32_32x32x16_bf16 v[50:65], v[10:13], v[14:17], v[50:65]
	ds_read_b128 v[6:9], v2 offset:60448
	ds_read_b128 v[10:13], v2 offset:65056
	s_waitcnt lgkmcnt(1)
	v_mfma_f32_32x32x16_bf16 v[34:49], v[6:9], v[14:17], v[34:49]
	s_waitcnt lgkmcnt(0)
	v_mfma_f32_32x32x16_bf16 v[18:33], v[10:13], v[14:17], v[18:33]
	ds_read_b128 v[6:9], v2 offset:51264
	ds_read_b128 v[10:13], v2 offset:55872
	v_add_f32_e64 v14, v82, -v4
	v_add_f32_e64 v15, v83, -v4
	v_exp_f32_e32 v82, v14
	v_exp_f32_e32 v83, v15
	v_sub_f32_e32 v14, v84, v4
	v_sub_f32_e32 v15, v85, v4
	v_exp_f32_e32 v84, v14
	v_exp_f32_e32 v85, v15
	v_sub_f32_e32 v14, v86, v4
	v_sub_f32_e32 v15, v87, v4
	v_exp_f32_e32 v86, v14
	v_exp_f32_e32 v87, v15
	v_sub_f32_e32 v14, v88, v4
	v_sub_f32_e32 v15, v89, v4
	v_cvt_pk_bf16_f32 v16, v86, v87
	v_exp_f32_e32 v88, v14
	v_exp_f32_e32 v89, v15
	v_cvt_pk_bf16_f32 v14, v82, v83
	v_cvt_pk_bf16_f32 v15, v84, v85
	v_cvt_pk_bf16_f32 v17, v88, v89
	s_waitcnt lgkmcnt(1)
	s_nop 0
	v_mfma_f32_32x32x16_bf16 v[66:81], v[6:9], v[14:17], v[66:81]
	s_waitcnt lgkmcnt(0)
	v_mfma_f32_32x32x16_bf16 v[50:65], v[10:13], v[14:17], v[50:65]
	ds_read_b128 v[6:9], v2 offset:60480
	ds_read_b128 v[10:13], v2 offset:65088
	s_waitcnt lgkmcnt(1)
	v_mfma_f32_32x32x16_bf16 v[34:49], v[6:9], v[14:17], v[34:49]
	s_waitcnt lgkmcnt(0)
	v_mfma_f32_32x32x16_bf16 v[18:33], v[10:13], v[14:17], v[18:33]
	ds_read_b128 v[6:9], v2 offset:51296
	ds_read_b128 v[10:13], v2 offset:55904
	v_add_f32_e64 v14, v90, -v4
	v_add_f32_e64 v15, v91, -v4
	v_exp_f32_e32 v90, v14
	v_exp_f32_e32 v91, v15
	v_sub_f32_e32 v14, v92, v4
	v_sub_f32_e32 v15, v93, v4
	v_exp_f32_e32 v92, v14
	v_exp_f32_e32 v93, v15
	v_sub_f32_e32 v14, v94, v4
	v_sub_f32_e32 v15, v95, v4
	v_exp_f32_e32 v94, v14
	v_exp_f32_e32 v95, v15
	v_sub_f32_e32 v14, v96, v4
	v_sub_f32_e32 v15, v97, v4
	v_cvt_pk_bf16_f32 v16, v94, v95
	v_exp_f32_e32 v96, v14
	v_exp_f32_e32 v97, v15
	v_cvt_pk_bf16_f32 v14, v90, v91
	v_cvt_pk_bf16_f32 v15, v92, v93
	v_cvt_pk_bf16_f32 v17, v96, v97
	s_waitcnt lgkmcnt(1)
	s_nop 0
	v_mfma_f32_32x32x16_bf16 v[66:81], v[6:9], v[14:17], v[66:81]
	v_add_f32_e64 v6, v98, 0
	v_add_f32_e64 v7, v99, 0
	v_add_f32_e32 v6, v100, v6
	v_add_f32_e32 v7, v101, v7
	v_add_f32_e32 v98, v102, v6
	v_add_f32_e32 v99, v103, v7
	ds_read_b128 v[6:9], v2 offset:60512
	s_waitcnt lgkmcnt(1)
	v_mfma_f32_32x32x16_bf16 v[50:65], v[10:13], v[14:17], v[50:65]
	v_add_f32_e32 v10, v104, v98
	v_add_f32_e32 v11, v105, v99
	v_add_f32_e32 v10, v106, v10
	v_add_f32_e32 v11, v107, v11
	v_add_f32_e32 v10, v108, v10
	v_add_f32_e32 v11, v109, v11
	v_add_f32_e32 v10, v110, v10
	v_add_f32_e32 v11, v111, v11
	v_add_f32_e32 v10, v112, v10
	v_add_f32_e32 v11, v113, v11
	v_add_f32_e32 v82, v82, v10
	v_add_f32_e32 v83, v83, v11
	ds_read_b128 v[10:13], v2 offset:65120
	s_waitcnt lgkmcnt(1)
	v_mfma_f32_32x32x16_bf16 v[34:49], v[6:9], v[14:17], v[34:49]
	v_add_f32_e32 v6, v84, v82
	v_add_f32_e32 v7, v85, v83
	v_add_f32_e32 v6, v86, v6
	v_add_f32_e32 v7, v87, v7
	v_add_f32_e32 v6, v88, v6
	v_add_f32_e32 v7, v89, v7
	v_add_f32_e32 v6, v90, v6
	v_add_f32_e32 v7, v91, v7
	s_waitcnt lgkmcnt(0)
	v_mfma_f32_32x32x16_bf16 v[18:33], v[10:13], v[14:17], v[18:33]
	v_add_f32_e32 v6, v92, v6
	v_add_f32_e32 v7, v93, v7
	v_add_f32_e32 v6, v94, v6
	v_add_f32_e32 v7, v95, v7
	v_add_f32_e32 v6, v96, v6
	v_add_f32_e32 v7, v97, v7
	v_add_f32_e32 v2, v6, v7
	v_add_f32_e32 v5, v5, v2
	s_mov_b32 s90, 0
	s_nop 7
	s_nop 7
